# RG-LRU in one pass: phase-4 lru publishes per-chunk (A,h) summaries and looks back over the previous 15 chunks via flags; phase-2 summary pass and phase-3 carry scan removed
# speedup vs baseline: 1.0203x; 1.0203x over previous
; template <int PASS> __device__ void lru_phase(const Params& p, unsigned char* smem) {
;     float* xcf = (float*)smem;
;     float* As = xcf + 64 * 132;
;     float* Us = As + 64 * 132;
;     float* qA = Us + 64 * 132;
;     float* qH = qA + 512;
;     const int tid = threadIdx.x, lane = tid & 63, wave = __builtin_amdgcn_readfirstlane(tid >> 6);
;     const u16* XR = (const u16*)(p.ws + OFF_XR);
;     u16* Y0 = (u16*)(p.ws + OFF_Y0);
;     const u16* LW = (const u16*)(p.ws + OFF_LRUW);
;     float* LA = (float*)(p.ws + OFF_LRUA); float* LH = (float*)(p.ws + OFF_LRUH); const float* LC = (const float*)(p.ws + OFF_LRUC);
;     const float* cw = p.in[3]; const float* cb = p.in[4];
;     u32x4 craw[2][4];
;     ...
;     if ((int)blockIdx.x < 4096) LRU_CLOAD((int)blockIdx.x);
.LBB0_310:
	v_and_b32_e32 v70, 0x3ff, v0
	v_lshl_or_b32 v70, s70, 9, v70
	v_cmp_gt_u32_e32 vcc, 0x2000, v70
	s_and_saveexec_b64 s[2:3], vcc
	s_cbranch_execz LRUX_zskip
	s_add_u32 s4, s64, 0x1f500000
	s_addc_u32 s5, s65, 0
	v_lshlrev_b32_e32 v70, 2, v70
	v_mov_b32_e32 v71, 0
	global_store_dword v70, v71, s[4:5] sc0 sc1
LRUX_zskip:
	s_or_b64 exec, exec, s[2:3]
	s_branch .LBB0_359
	s_add_u32 s0, s64, 0x4000000
	s_addc_u32 s1, s65, 0
	s_cmpk_lt_i32 s70, 0x1000
	s_cselect_b64 s[2:3], -1, 0
	s_cmpk_gt_i32 s70, 0xfff
	s_waitcnt lgkmcnt(0)
	v_readfirstlane_b32 s6, v1
	s_cbranch_scc1 .LBB0_320
	s_lshl_b32 s4, s70, 7
	v_lshlrev_b32_e32 v3, 3, v1
	s_and_b32 s4, s4, 0x780
	v_and_b32_e32 v3, 0x78, v3
	v_or_b32_e32 v3, s4, v3
	s_lshl_b32 s4, s70, 2
	v_lshrrev_b32_e32 v2, 4, v1
	s_and_b32 s5, s4, 0xfc0
	v_or_b32_e32 v14, s5, v2
	v_lshlrev_b32_e32 v2, 1, v3
	v_mov_b32_e32 v3, 0
	v_mov_b32_e32 v4, v3
	v_mov_b32_e32 v5, v3
	v_add_u32_e32 v15, -3, v14
	v_lshl_add_u64 v[30:31], s[0:1], 0, v[2:3]
	v_mov_b32_e32 v2, v3
	s_waitcnt vmcnt(0)
	v_mov_b64_e32 v[8:9], v[4:5]
	s_and_b32 s7, s4, 0xfffff000
	v_cmp_lt_i32_e32 vcc, -1, v15
	v_mov_b64_e32 v[6:7], v[2:3]
	s_and_saveexec_b64 s[4:5], vcc
	s_cbranch_execz .LBB0_313
	v_add_u32_e32 v6, s7, v15
	v_ashrrev_i32_e32 v7, 31, v6
	v_lshlrev_b64 v[6:7], 12, v[6:7]
	v_lshl_add_u64 v[6:7], v[30:31], 0, v[6:7]
	global_load_dwordx4 v[6:9], v[6:7], off

; __device__ void lru_carry(const Params& p) {
;     const float* LA = (const float*)(p.ws + OFF_LRUA); const float* LH = (const float*)(p.ws + OFF_LRUH); float* LC = (float*)(p.ws + OFF_LRUC);
;     for (int idx = blockIdx.x * 512 + threadIdx.x; idx < 4 * 2048; idx += gridDim.x * 512) { const int b = idx >> 11, cg_ = idx & 2047; float c = 0.f;
; #pragma unroll 8
;         for (int k = 0; k < 64; ++k) { const size_t o = (size_t)(b * 64 + k) * 2048 + cg_; LC[o] = c; c = LA[o] * c + LH[o]; } }
; }
.LBB0_371:
	s_cmp_lt_i32 s66, 4
	s_cselect_b64 s[2:3], -1, 0
	s_and_b64 s[0:1], s[2:3], s[0:1]
	s_andn2_b64 vcc, exec, s[0:1]
	s_cbranch_vccnz .LBB0_399
	s_waitcnt vmcnt(0)
	v_and_b32_e32 v4, 0x3ff, v0
	v_lshl_or_b32 v1, s70, 9, v4
	s_movk_i32 s2, 0
	v_cmp_gt_i32_e32 vcc, s2, v1
	s_and_saveexec_b64 s[16:17], vcc
	s_cbranch_execz .LBB0_377
	s_lshl_b32 s2, s70, 9
	s_waitcnt lgkmcnt(0)
	s_lshl_b32 s22, s62, 9
	v_add_u16_e32 v5, s2, v4
	s_mov_b64 s[18:19], 0
	s_movk_i32 s23, 0x1fff

; __device__ __forceinline__ float softplusf_(float x) { return fmaxf(x, 0.f) + log1pf(__expf(-fabsf(x))); }
; __device__ __forceinline__ float fsig0(float x) { return __builtin_amdgcn_rcpf(1.0f + __expf(-x)); }
; template <int PASS> __device__ void lru_phase(const Params& p, unsigned char* smem) {
;     ...
;         {
;             const int ch = 16 * wave + (lane & 15), cgl = jb * 128 + ch;
;             const float ba_ = jb_fixed ? hb_a : p.in[6][cgl], bx_ = jb_fixed ? hb_x : p.in[8][cgl], sp = jb_fixed ? hsp : softplusf_(-p.in[9][cgl]);
; #pragma unroll
;             for (int m = 0; m < 4; ++m)
; #pragma unroll
;                 for (int r = 0; r < 4; ++r) { const int t = 16 * m + 4 * (lane >> 4) + r;
;                     const float rg = fsig0(accA[m][r] + ba_), ig = fsig0(accX[m][r] + bx_);
;                     const float la = -8.0f * rg * sp, a = __expf(la), u = __builtin_amdgcn_sqrtf(fmaxf(1.0f - a * a, 0.f)) * (ig * xcf[t * 132 + ch]);
;                     As[t * 132 + ch] = a; Us[t * 132 + ch] = u; }
;         }
.LBB0_572:
	s_waitcnt vmcnt(0)
	v_add_f32_e32 v66, v96, v100
	v_add_f32_e32 v96, v97, v100
	v_mul_f32_e32 v96, 0xbfb8aa3b, v96
	v_exp_f32_e32 v96, v96
	v_mul_f32_e32 v66, 0xbfb8aa3b, v66
	v_exp_f32_e32 v66, v66
	v_add_f32_e32 v93, v93, v101
	v_add_f32_e32 v96, 1.0, v96
	v_rcp_f32_e32 v96, v96
	v_add_f32_e32 v66, 1.0, v66
	v_mul_f32_e32 v93, 0xbfb8aa3b, v93
	v_rcp_f32_e32 v66, v66
	v_mul_f32_e32 v96, 0xc1000000, v96
	v_mul_f32_e32 v96, v96, v102
	v_mul_f32_e32 v96, 0x3fb8aa3b, v96
	v_exp_f32_e32 v93, v93
	v_exp_f32_e32 v96, v96
	ds_read2_b32 v[104:105], v141 offset1:132
	v_mul_f32_e32 v66, 0xc1000000, v66
	v_add_f32_e32 v93, 1.0, v93
	v_fma_f32 v103, -v96, v96, 1.0
	v_mul_f32_e32 v66, v66, v102
	v_rcp_f32_e32 v93, v93
	v_max_f32_e32 v103, 0, v103
	v_add_f32_e32 v98, v98, v100
	v_mul_f32_e32 v66, 0x3fb8aa3b, v66
	v_sqrt_f32_e32 v103, v103
	v_mul_f32_e32 v98, 0xbfb8aa3b, v98
	v_exp_f32_e32 v66, v66
	v_exp_f32_e32 v98, v98
	s_waitcnt lgkmcnt(0)
	v_mul_f32_e32 v93, v93, v105
	v_mul_f32_e32 v93, v93, v103
	v_add_u32_e32 v103, 0x8400, v141
	v_fma_f32 v97, -v66, v66, 1.0
	ds_write2_b32 v103, v66, v96 offset1:132
	v_add_f32_e32 v66, 1.0, v98
	v_rcp_f32_e32 v66, v66
	v_add_f32_e32 v94, v94, v101
	v_add_f32_e32 v98, v99, v100
	v_mul_f32_e32 v94, 0xbfb8aa3b, v94
	v_mul_f32_e32 v66, 0xc1000000, v66
	v_mul_f32_e32 v66, v66, v102
	v_mul_f32_e32 v66, 0x3fb8aa3b, v66
	v_mul_f32_e32 v98, 0xbfb8aa3b, v98
	v_exp_f32_e32 v94, v94
	v_exp_f32_e32 v66, v66
	v_exp_f32_e32 v98, v98
	ds_write_b32 v143, v93
	v_add_f32_e32 v93, 1.0, v94
	v_fma_f32 v94, -v66, v66, 1.0
	ds_read_b32 v96, v141 offset:1056
	ds_write_b32 v141, v66 offset:34848
	v_add_f32_e32 v66, 1.0, v98
	v_rcp_f32_e32 v93, v93
	v_max_f32_e32 v94, 0, v94
	v_rcp_f32_e32 v66, v66
	v_sqrt_f32_e32 v94, v94
	s_waitcnt lgkmcnt(1)
	v_mul_f32_e32 v93, v93, v96
	v_add_f32_e32 v88, v88, v100
	v_mul_f32_e32 v66, 0xc1000000, v66
	v_mul_f32_e32 v93, v94, v93
	v_add_f32_e32 v94, v95, v101
	v_mul_f32_e32 v66, v66, v102
	v_mul_f32_e32 v94, 0xbfb8aa3b, v94
	v_mul_f32_e32 v66, 0x3fb8aa3b, v66
	v_mul_f32_e32 v88, 0xbfb8aa3b, v88
	v_exp_f32_e32 v94, v94
	v_exp_f32_e32 v66, v66
	v_exp_f32_e32 v88, v88
	ds_write_b32 v144, v93
	v_add_f32_e32 v93, 1.0, v94
	v_fma_f32 v94, -v66, v66, 1.0
	ds_write_b32 v141, v66 offset:35376
	v_add_f32_e32 v66, 1.0, v88
	v_rcp_f32_e32 v66, v66
	ds_read_b32 v95, v141 offset:1584
	v_rcp_f32_e32 v93, v93
	v_max_f32_e32 v94, 0, v94
	v_mul_f32_e32 v66, 0xc1000000, v66
	v_mul_f32_e32 v66, v66, v102
	v_add_f32_e32 v89, v89, v100
	v_sqrt_f32_e32 v94, v94
	v_mul_f32_e32 v66, 0x3fb8aa3b, v66
	v_mul_f32_e32 v89, 0xbfb8aa3b, v89
	v_exp_f32_e32 v66, v66
	v_exp_f32_e32 v89, v89
	s_waitcnt lgkmcnt(0)
	v_mul_f32_e32 v93, v93, v95
	v_add_f32_e32 v84, v84, v101
	v_mul_f32_e32 v93, v94, v93
	v_mul_f32_e32 v84, 0xbfb8aa3b, v84
	v_exp_f32_e32 v84, v84
	ds_write_b32 v145, v93
	v_fma_f32 v88, -v66, v66, 1.0
	ds_write_b32 v141, v66 offset:42240
	v_add_f32_e32 v66, 1.0, v89
	v_rcp_f32_e32 v66, v66
	v_add_f32_e32 v84, 1.0, v84
	ds_read_b32 v93, v141 offset:8448
	v_rcp_f32_e32 v84, v84
	v_max_f32_e32 v88, 0, v88
	v_mul_f32_e32 v66, 0xc1000000, v66
	v_sqrt_f32_e32 v88, v88
	v_add_f32_e32 v85, v85, v101
	v_mul_f32_e32 v66, v66, v102
	v_add_f32_e32 v89, v90, v100
	v_mul_f32_e32 v85, 0xbfb8aa3b, v85
	v_mul_f32_e32 v66, 0x3fb8aa3b, v66
	v_mul_f32_e32 v89, 0xbfb8aa3b, v89
	v_exp_f32_e32 v85, v85
	v_exp_f32_e32 v66, v66
	v_exp_f32_e32 v89, v89
	s_waitcnt lgkmcnt(0)
	v_mul_f32_e32 v84, v84, v93
	v_mul_f32_e32 v84, v88, v84
	ds_write_b32 v146, v84
	v_add_f32_e32 v84, 1.0, v85
	v_fma_f32 v85, -v66, v66, 1.0
	ds_read_b32 v88, v141 offset:8976
	ds_write_b32 v141, v66 offset:42768
	v_add_f32_e32 v66, 1.0, v89
	v_rcp_f32_e32 v84, v84
	v_max_f32_e32 v85, 0, v85
	v_rcp_f32_e32 v66, v66
	v_sqrt_f32_e32 v85, v85
	s_waitcnt lgkmcnt(1)
	v_mul_f32_e32 v84, v84, v88
	v_add_f32_e32 v88, v91, v100
	v_mul_f32_e32 v66, 0xc1000000, v66
	v_mul_f32_e32 v84, v85, v84
	v_add_f32_e32 v85, v86, v101
	v_mul_f32_e32 v66, v66, v102
	v_mul_f32_e32 v85, 0xbfb8aa3b, v85
	v_mul_f32_e32 v66, 0x3fb8aa3b, v66
	v_mul_f32_e32 v88, 0xbfb8aa3b, v88
	v_exp_f32_e32 v85, v85
	v_exp_f32_e32 v66, v66
	v_exp_f32_e32 v88, v88
	ds_write_b32 v147, v84
	v_add_f32_e32 v84, 1.0, v85
	v_fma_f32 v85, -v66, v66, 1.0
	ds_read_b32 v86, v141 offset:9504
	ds_write_b32 v141, v66 offset:43296
	v_add_f32_e32 v66, 1.0, v88
	v_rcp_f32_e32 v84, v84
	v_max_f32_e32 v85, 0, v85
	v_rcp_f32_e32 v66, v66
	v_sqrt_f32_e32 v85, v85
	s_waitcnt lgkmcnt(1)
	v_mul_f32_e32 v84, v84, v86
	v_add_f32_e32 v80, v80, v100
	v_mul_f32_e32 v66, 0xc1000000, v66
	v_mul_f32_e32 v84, v85, v84
	v_add_f32_e32 v85, v87, v101
	v_mul_f32_e32 v66, v66, v102
	v_mul_f32_e32 v85, 0xbfb8aa3b, v85
	v_mul_f32_e32 v66, 0x3fb8aa3b, v66
	v_mul_f32_e32 v80, 0xbfb8aa3b, v80
	v_exp_f32_e32 v85, v85
	v_exp_f32_e32 v66, v66
	v_exp_f32_e32 v80, v80
	ds_write_b32 v148, v84
	v_add_f32_e32 v84, 1.0, v85
	v_fma_f32 v85, -v66, v66, 1.0
	ds_write_b32 v141, v66 offset:43824
	v_add_f32_e32 v66, 1.0, v80
	v_rcp_f32_e32 v66, v66
	ds_read_b32 v86, v141 offset:10032
	v_rcp_f32_e32 v84, v84
	v_max_f32_e32 v85, 0, v85
	v_mul_f32_e32 v66, 0xc1000000, v66
	v_mul_f32_e32 v66, v66, v102
	v_add_f32_e32 v81, v81, v100
	v_sqrt_f32_e32 v85, v85
	v_mul_f32_e32 v66, 0x3fb8aa3b, v66
	v_mul_f32_e32 v81, 0xbfb8aa3b, v81
	v_exp_f32_e32 v66, v66
	v_exp_f32_e32 v81, v81
	s_waitcnt lgkmcnt(0)
; __device__ __forceinline__ float softplusf_(float x) { return fmaxf(x, 0.f) + log1pf(__expf(-fabsf(x))); }
; #define LBAR0() do { asm volatile("s_waitcnt lgkmcnt(0)" ::: "memory"); __builtin_amdgcn_s_barrier(); asm volatile("" ::: "memory"); } while (0)
; __device__ __forceinline__ float fsig0(float x) { return __builtin_amdgcn_rcpf(1.0f + __expf(-x)); }
; template <int PASS> __device__ void lru_phase(const Params& p, unsigned char* smem) {
;     ...
;         {
;             const int ch = 16 * wave + (lane & 15), cgl = jb * 128 + ch;
;             const float ba_ = jb_fixed ? hb_a : p.in[6][cgl], bx_ = jb_fixed ? hb_x : p.in[8][cgl], sp = jb_fixed ? hsp : softplusf_(-p.in[9][cgl]);
; #pragma unroll
;             for (int m = 0; m < 4; ++m)
; #pragma unroll
;                 for (int r = 0; r < 4; ++r) { const int t = 16 * m + 4 * (lane >> 4) + r;
;                     const float rg = fsig0(accA[m][r] + ba_), ig = fsig0(accX[m][r] + bx_);
;                     const float la = -8.0f * rg * sp, a = __expf(la), u = __builtin_amdgcn_sqrtf(fmaxf(1.0f - a * a, 0.f)) * (ig * xcf[t * 132 + ch]);
;                     As[t * 132 + ch] = a; Us[t * 132 + ch] = u; }
;         }
;         LBAR0();
	v_mul_f32_e32 v84, v84, v86
	v_add_f32_e32 v76, v76, v101
	v_mul_f32_e32 v84, v85, v84
	v_mul_f32_e32 v76, 0xbfb8aa3b, v76
	v_exp_f32_e32 v76, v76
	ds_write_b32 v149, v84
	v_fma_f32 v80, -v66, v66, 1.0
	ds_write_b32 v141, v66 offset:50688
	v_add_f32_e32 v66, 1.0, v81
	v_rcp_f32_e32 v66, v66
	v_add_f32_e32 v76, 1.0, v76
	ds_read_b32 v84, v141 offset:16896
	v_rcp_f32_e32 v76, v76
	v_max_f32_e32 v80, 0, v80
	v_mul_f32_e32 v66, 0xc1000000, v66
	v_sqrt_f32_e32 v80, v80
	v_add_f32_e32 v77, v77, v101
	v_mul_f32_e32 v66, v66, v102
	v_add_f32_e32 v81, v82, v100
	v_mul_f32_e32 v77, 0xbfb8aa3b, v77
	v_mul_f32_e32 v66, 0x3fb8aa3b, v66
	v_mul_f32_e32 v81, 0xbfb8aa3b, v81
	v_exp_f32_e32 v77, v77
	v_exp_f32_e32 v66, v66
	v_exp_f32_e32 v81, v81
	s_waitcnt lgkmcnt(0)
	v_mul_f32_e32 v76, v76, v84
	v_mul_f32_e32 v76, v80, v76
	ds_write_b32 v150, v76
	v_add_f32_e32 v76, 1.0, v77
	v_fma_f32 v77, -v66, v66, 1.0
	ds_read_b32 v80, v141 offset:17424
	ds_write_b32 v141, v66 offset:51216
	v_add_f32_e32 v66, 1.0, v81
	v_rcp_f32_e32 v76, v76
	v_max_f32_e32 v77, 0, v77
	v_rcp_f32_e32 v66, v66
	v_sqrt_f32_e32 v77, v77
	s_waitcnt lgkmcnt(1)
	v_mul_f32_e32 v76, v76, v80
	v_add_f32_e32 v80, v83, v100
	v_mul_f32_e32 v66, 0xc1000000, v66
	v_mul_f32_e32 v76, v77, v76
	v_add_f32_e32 v77, v78, v101
	v_mul_f32_e32 v66, v66, v102
	v_mul_f32_e32 v77, 0xbfb8aa3b, v77
	v_mul_f32_e32 v66, 0x3fb8aa3b, v66
	v_mul_f32_e32 v80, 0xbfb8aa3b, v80
	v_exp_f32_e32 v77, v77
	v_exp_f32_e32 v66, v66
	v_exp_f32_e32 v80, v80
	ds_write_b32 v151, v76
	v_add_f32_e32 v76, 1.0, v77
	v_fma_f32 v77, -v66, v66, 1.0
	ds_read_b32 v78, v141 offset:17952
	ds_write_b32 v141, v66 offset:51744
	v_add_f32_e32 v66, 1.0, v80
	v_rcp_f32_e32 v76, v76
	v_max_f32_e32 v77, 0, v77
	v_rcp_f32_e32 v66, v66
	v_sqrt_f32_e32 v77, v77
	s_waitcnt lgkmcnt(1)
	v_mul_f32_e32 v76, v76, v78
	v_add_f32_e32 v72, v72, v100
	v_mul_f32_e32 v66, 0xc1000000, v66
	v_mul_f32_e32 v76, v77, v76
	v_add_f32_e32 v77, v79, v101
	v_mul_f32_e32 v66, v66, v102
	v_mul_f32_e32 v77, 0xbfb8aa3b, v77
	v_mul_f32_e32 v66, 0x3fb8aa3b, v66
	v_mul_f32_e32 v72, 0xbfb8aa3b, v72
	v_exp_f32_e32 v77, v77
	v_exp_f32_e32 v66, v66
	v_exp_f32_e32 v72, v72
	ds_write_b32 v152, v76
	v_add_f32_e32 v76, 1.0, v77
	v_fma_f32 v77, -v66, v66, 1.0
	ds_write_b32 v141, v66 offset:52272
	v_add_f32_e32 v66, 1.0, v72
	v_rcp_f32_e32 v66, v66
	ds_read_b32 v78, v141 offset:18480
	v_rcp_f32_e32 v76, v76
	v_max_f32_e32 v77, 0, v77
	v_mul_f32_e32 v66, 0xc1000000, v66
	v_mul_f32_e32 v66, v66, v102
	v_add_f32_e32 v73, v73, v100
	v_sqrt_f32_e32 v77, v77
	v_mul_f32_e32 v66, 0x3fb8aa3b, v66
	v_mul_f32_e32 v73, 0xbfb8aa3b, v73
	v_exp_f32_e32 v66, v66
	v_exp_f32_e32 v73, v73
	s_waitcnt lgkmcnt(0)
	v_mul_f32_e32 v76, v76, v78
	v_add_f32_e32 v68, v68, v101
	v_mul_f32_e32 v76, v77, v76
	v_mul_f32_e32 v68, 0xbfb8aa3b, v68
	v_exp_f32_e32 v68, v68
	ds_write_b32 v153, v76
	v_fma_f32 v72, -v66, v66, 1.0
	ds_write_b32 v141, v66 offset:59136
	v_add_f32_e32 v66, 1.0, v73
	v_rcp_f32_e32 v66, v66
	v_add_f32_e32 v68, 1.0, v68
	ds_read_b32 v76, v141 offset:25344
	v_rcp_f32_e32 v68, v68
	v_max_f32_e32 v72, 0, v72
	v_mul_f32_e32 v66, 0xc1000000, v66
	v_sqrt_f32_e32 v72, v72
	v_add_f32_e32 v69, v69, v101
	v_mul_f32_e32 v66, v66, v102
	v_add_f32_e32 v73, v74, v100
	v_mul_f32_e32 v69, 0xbfb8aa3b, v69
	v_mul_f32_e32 v66, 0x3fb8aa3b, v66
	v_mul_f32_e32 v73, 0xbfb8aa3b, v73
	v_exp_f32_e32 v69, v69
	v_exp_f32_e32 v66, v66
	v_exp_f32_e32 v73, v73
	s_waitcnt lgkmcnt(0)
	v_mul_f32_e32 v68, v68, v76
	v_mul_f32_e32 v68, v72, v68
	ds_write_b32 v154, v68
	v_add_f32_e32 v68, 1.0, v69
	v_fma_f32 v69, -v66, v66, 1.0
	ds_read_b32 v72, v141 offset:25872
	ds_write_b32 v141, v66 offset:59664
	v_add_f32_e32 v66, 1.0, v73
	v_rcp_f32_e32 v68, v68
	v_max_f32_e32 v69, 0, v69
	v_rcp_f32_e32 v66, v66
	v_sqrt_f32_e32 v69, v69
	s_waitcnt lgkmcnt(1)
	v_mul_f32_e32 v68, v68, v72
	v_add_f32_e32 v72, v75, v100
	v_mul_f32_e32 v66, 0xc1000000, v66
	v_mul_f32_e32 v68, v69, v68
	v_add_f32_e32 v69, v70, v101
	v_mul_f32_e32 v66, v66, v102
	v_mul_f32_e32 v69, 0xbfb8aa3b, v69
	v_mul_f32_e32 v66, 0x3fb8aa3b, v66
	v_mul_f32_e32 v72, 0xbfb8aa3b, v72
	v_exp_f32_e32 v69, v69
	v_exp_f32_e32 v66, v66
	v_exp_f32_e32 v72, v72
	ds_write_b32 v155, v68
	v_add_f32_e32 v68, 1.0, v69
	v_fma_f32 v69, -v66, v66, 1.0
	ds_read_b32 v70, v141 offset:26400
	ds_write_b32 v141, v66 offset:60192
	v_add_f32_e32 v66, 1.0, v72
	v_rcp_f32_e32 v68, v68
	v_max_f32_e32 v69, 0, v69
	v_rcp_f32_e32 v66, v66
	v_sqrt_f32_e32 v69, v69
	v_add_f32_e32 v92, v92, v101
	s_waitcnt lgkmcnt(1)
	v_mul_f32_e32 v68, v68, v70
	v_mul_f32_e32 v66, 0xc1000000, v66
	v_mul_f32_e32 v92, 0xbfb8aa3b, v92
	v_mul_f32_e32 v68, v69, v68
	v_add_f32_e32 v69, v71, v101
	v_mul_f32_e32 v66, v66, v102
	v_exp_f32_e32 v92, v92
	v_mul_f32_e32 v69, 0xbfb8aa3b, v69
	v_mul_f32_e32 v66, 0x3fb8aa3b, v66
	v_exp_f32_e32 v69, v69
	v_exp_f32_e32 v66, v66
	v_add_f32_e32 v92, 1.0, v92
	ds_write_b32 v156, v68
	v_rcp_f32_e32 v92, v92
	v_max_f32_e32 v97, 0, v97
	v_add_f32_e32 v68, 1.0, v69
	v_fma_f32 v69, -v66, v66, 1.0
	ds_read_b32 v70, v141 offset:26928
	v_sqrt_f32_e32 v97, v97
	v_rcp_f32_e32 v68, v68
	v_max_f32_e32 v69, 0, v69
	v_sqrt_f32_e32 v69, v69
	v_mul_f32_e32 v92, v92, v104
	v_mul_f32_e32 v71, v92, v97
	s_waitcnt lgkmcnt(0)
	v_mul_f32_e32 v68, v68, v70
	ds_write_b32 v142, v71
	v_mul_f32_e32 v68, v69, v68
	ds_write_b32 v141, v66 offset:60720
	ds_write_b32 v157, v68
	s_waitcnt lgkmcnt(0)
	s_barrier
; #define LBAR0() do { asm volatile("s_waitcnt lgkmcnt(0)" ::: "memory"); __builtin_amdgcn_s_barrier(); asm volatile("" ::: "memory"); } while (0)
; template <int PASS> __device__ void lru_phase(const Params& p, unsigned char* smem) {
;     ...
;         const int ch = tid & 127, q = tid >> 7, cgl = jb * 128 + ch;
;         { float h = 0.f, A = 1.f;
; #pragma unroll
;           for (int tt = 0; tt < 16; ++tt) { const int t = q * 16 + tt; const float a = As[t * 132 + ch], u = Us[t * 132 + ch]; h = a * h + u; A *= a;
;               if (PASS == 2) { Us[t * 132 + ch] = h; As[t * 132 + ch] = A; } }
;           qA[q * 128 + ch] = A; qH[q * 128 + ch] = h; }
;         LBAR0();
;         if (PASS == 1) {
;             if (q == 0) { float h = 0.f, A = 1.f;
; #pragma unroll
;                 for (int qq = 0; qq < 4; ++qq) { h = qA[qq * 128 + ch] * h + qH[qq * 128 + ch]; A *= qA[qq * 128 + ch]; }
;                 LA[(size_t)(b * 64 + c) * 2048 + cgl] = A; LH[(size_t)(b * 64 + c) * 2048 + cgl] = h; }
;         } else {
;             float carry = LC[(size_t)(b * 64 + c) * 2048 + cgl];
;             for (int qq = 0; qq < q; ++qq) carry = qA[qq * 128 + ch] * carry + qH[qq * 128 + ch];
	ds_read_b32 v66, v158 offset:33792
	ds_read_b32 v68, v1
	s_lshl_b32 s4, s25, 6
	s_or_b32 s4, s4, s24
	s_ashr_i32 s5, s4, 31
	s_lshl_b64 s[4:5], s[4:5], 13
	s_waitcnt lgkmcnt(0)
	v_fmac_f32_e32 v68, 0, v66
	ds_write_b32 v1, v68
	ds_read_b32 v69, v160 offset:33792
	ds_read_b32 v70, v161
	s_add_u32 s4, s26, s4
	s_addc_u32 s5, s27, s5
	s_waitcnt lgkmcnt(1)
	v_mul_f32_e32 v66, v66, v69
	s_waitcnt lgkmcnt(0)
	v_fmac_f32_e32 v70, v68, v69
	ds_write_b32 v161, v70
	ds_write_b32 v160, v66 offset:33792
	ds_read_b32 v68, v163 offset:33792
	ds_read_b32 v69, v164
	s_waitcnt lgkmcnt(1)
	v_mul_f32_e32 v66, v66, v68
	s_waitcnt lgkmcnt(0)
	v_fmac_f32_e32 v69, v70, v68
	ds_write_b32 v164, v69
	ds_write_b32 v163, v66 offset:33792
	ds_read_b32 v68, v166 offset:33792
	ds_read_b32 v70, v167
	s_waitcnt lgkmcnt(1)
	v_mul_f32_e32 v66, v66, v68
	s_waitcnt lgkmcnt(0)
	v_fmac_f32_e32 v70, v69, v68
	ds_write_b32 v167, v70
	ds_write_b32 v166, v66 offset:33792
	ds_read_b32 v68, v169 offset:33792
	ds_read_b32 v69, v170
	s_waitcnt lgkmcnt(1)
	v_mul_f32_e32 v66, v66, v68
	s_waitcnt lgkmcnt(0)
	v_fmac_f32_e32 v69, v70, v68
	ds_write_b32 v170, v69
	ds_write_b32 v169, v66 offset:33792
	ds_read_b32 v68, v172 offset:33792
	ds_read_b32 v70, v173
	s_waitcnt lgkmcnt(1)
	v_mul_f32_e32 v66, v66, v68
	s_waitcnt lgkmcnt(0)
	v_fmac_f32_e32 v70, v69, v68
	ds_write_b32 v173, v70
	ds_write_b32 v172, v66 offset:33792
	ds_read_b32 v68, v175 offset:33792
	ds_read_b32 v69, v176
	s_waitcnt lgkmcnt(1)
	v_mul_f32_e32 v66, v66, v68
	s_waitcnt lgkmcnt(0)
	v_fmac_f32_e32 v69, v70, v68
	ds_write_b32 v176, v69
	ds_write_b32 v175, v66 offset:33792
	ds_read_b32 v68, v178 offset:33792
	ds_read_b32 v70, v179
	s_waitcnt lgkmcnt(1)
	v_mul_f32_e32 v66, v66, v68
	s_waitcnt lgkmcnt(0)
	v_fmac_f32_e32 v70, v69, v68
	ds_write_b32 v179, v70
	ds_write_b32 v178, v66 offset:33792
	ds_read_b32 v68, v181 offset:33792
	ds_read_b32 v69, v182
	s_waitcnt lgkmcnt(1)
	v_mul_f32_e32 v66, v66, v68
	s_waitcnt lgkmcnt(0)
	v_fmac_f32_e32 v69, v70, v68
	ds_write_b32 v182, v69
	ds_write_b32 v181, v66 offset:33792
	ds_read_b32 v68, v184 offset:33792
	ds_read_b32 v70, v185
	s_waitcnt lgkmcnt(1)
	v_mul_f32_e32 v66, v66, v68
	s_waitcnt lgkmcnt(0)
	v_fmac_f32_e32 v70, v69, v68
	ds_write_b32 v185, v70
	ds_write_b32 v184, v66 offset:33792
	ds_read_b32 v68, v187 offset:33792
	ds_read_b32 v69, v188
	s_waitcnt lgkmcnt(1)
	v_mul_f32_e32 v66, v66, v68
	s_waitcnt lgkmcnt(0)
	v_fmac_f32_e32 v69, v70, v68
	ds_write_b32 v188, v69
	ds_write_b32 v187, v66 offset:33792
	ds_read_b32 v68, v190 offset:33792
	ds_read_b32 v70, v191
	s_waitcnt lgkmcnt(1)
	v_mul_f32_e32 v66, v66, v68
	s_waitcnt lgkmcnt(0)
	v_fmac_f32_e32 v70, v69, v68
	ds_write_b32 v191, v70
	ds_write_b32 v190, v66 offset:33792
	ds_read_b32 v68, v193 offset:33792
	ds_read_b32 v69, v194
	s_waitcnt lgkmcnt(1)
	v_mul_f32_e32 v66, v66, v68
	s_waitcnt lgkmcnt(0)
	v_fmac_f32_e32 v69, v70, v68
	ds_write_b32 v194, v69
	ds_write_b32 v193, v66 offset:33792
	ds_read_b32 v68, v196 offset:33792
	ds_read_b32 v70, v197
	s_waitcnt lgkmcnt(1)
	v_mul_f32_e32 v66, v66, v68
	s_waitcnt lgkmcnt(0)
	v_fmac_f32_e32 v70, v69, v68
	ds_write_b32 v197, v70
	ds_write_b32 v196, v66 offset:33792
	ds_read_b32 v68, v199 offset:33792
	ds_read_b32 v69, v200
	s_waitcnt lgkmcnt(1)
	v_mul_f32_e32 v66, v66, v68
	s_waitcnt lgkmcnt(0)
	v_fmac_f32_e32 v69, v70, v68
	ds_write_b32 v200, v69
	ds_write_b32 v199, v66 offset:33792
	ds_read_b32 v68, v202 offset:33792
	ds_read_b32 v70, v203
	s_waitcnt lgkmcnt(0)
	v_fmac_f32_e32 v70, v69, v68
	v_mul_f32_e32 v68, v66, v68
	ds_write_b32 v203, v70
	ds_write_b32 v202, v68 offset:33792
	v_or_b32_e32 v66, s39, v132
	ds_write_b32 v139, v68
	ds_write_b32 v140, v70
	s_waitcnt lgkmcnt(0)
	s_barrier
	v_lshlrev_b32_e32 v68, 2, v66
	s_sub_i32 s40, s37, s62
	s_bfe_u32 s41, s40, 0x60004
	s_lshr_b32 s42, s40, 10
	s_and_b32 s43, s40, 15
	s_lshl_b32 s44, s42, 6
	s_or_b32 s44, s44, s41
	s_add_u32 s48, s64, 0x1f100000
	s_addc_u32 s49, s65, 0
	s_add_u32 s50, s64, 0x1f300000
	s_addc_u32 s51, s65, 0
	s_add_u32 s52, s64, 0x1f500000
	s_addc_u32 s53, s65, 0
	v_add_u32_e32 v71, 0xfffff800, v205
	ds_read_b32 v72, v71
	ds_read_b32 v73, v71 offset:512
	ds_read_b32 v74, v71 offset:1024
	ds_read_b32 v75, v71 offset:1536
	ds_read_b32 v76, v71 offset:2048
	ds_read_b32 v77, v71 offset:2560
	ds_read_b32 v78, v71 offset:3072
	ds_read_b32 v79, v71 offset:3584
	v_bfe_u32 v85, v0, 6, 3
	s_lshl_b32 s45, s44, 13
	v_add_u32_e32 v82, s45, v68
	s_nop 1
	v_readfirstlane_b32 s47, v85
	s_and_b32 s46, s47, 1
	s_lshl_b32 s54, s43, 3
	s_lshl_b32 s46, s46, 2
	s_add_i32 s54, s54, s46
	s_waitcnt lgkmcnt(0)
	v_fma_f32 v80, v73, v76, v77
	v_mul_f32_e32 v81, v72, v73
	v_fma_f32 v80, v74, v80, v78
	v_mul_f32_e32 v81, v81, v74
	v_fma_f32 v80, v75, v80, v79
	v_mul_f32_e32 v81, v81, v75
	s_cmp_lt_u32 s47, 2
	s_cbranch_scc0 LRUX_nopub
	global_store_dword v82, v81, s[48:49] sc0 sc1
	global_store_dword v82, v80, s[50:51] sc0 sc1
	s_lshl_b32 s46, s44, 7
	s_add_i32 s46, s46, s54
	v_mov_b32_e32 v83, 1
	v_mov_b32_e32 v84, s46
	s_waitcnt vmcnt(0)
	global_store_dword v84, v83, s[52:53] sc0 sc1
; template <int PASS> __device__ void lru_phase(const Params& p, unsigned char* smem) {
;     ...
;         } else {
;             float carry = LC[(size_t)(b * 64 + c) * 2048 + cgl];
;             for (int qq = 0; qq < q; ++qq) carry = qA[qq * 128 + ch] * carry + qH[qq * 128 + ch];
LRUX_nopub:
	s_cmp_lt_u32 s41, 16
	s_cbranch_scc0 LRUX_keepP
	v_mov_b32_e32 v252, 0
LRUX_keepP:
	v_mbcnt_lo_u32_b32 v86, -1, 0
	v_mbcnt_hi_u32_b32 v86, -1, v86
	s_add_i32 s55, s41, -1
	v_sub_u32_e32 v87, s55, v86
	v_cmp_gt_u32_e32 vcc, 15, v86
	v_cmp_le_i32_e64 s[56:57], 0, v87
	s_and_b64 s[56:57], vcc, s[56:57]
	s_lshl_b32 s58, s42, 6
	v_add_u32_e32 v88, s58, v87
	v_lshlrev_b32_e32 v88, 7, v88
	v_add_u32_e32 v88, s54, v88
	s_mov_b64 s[76:77], exec
	s_cmp_eq_u64 s[56:57], 0
	s_cbranch_scc1 LRUX_polled
	s_mov_b64 exec, s[56:57]
	s_movk_i32 s59, 0x400
LRUX_poll:
	global_load_dword v89, v88, s[52:53] sc0 sc1
	s_waitcnt vmcnt(0)
	v_cmp_ne_u32_e32 vcc, 1, v89
	s_cbranch_vccz LRUX_pollend
	s_add_i32 s59, s59, -1
	s_cmp_eq_u32 s59, 0
	s_cbranch_scc1 LRUX_pollend
	s_sleep 1
	s_branch LRUX_poll
LRUX_pollend:
	s_mov_b64 exec, s[76:77]
LRUX_polled:
	s_cmp_lt_u32 s41, 1
	s_cselect_b32 s58, 0, 0x2000
	v_subrev_u32_e32 v87, s58, v82
	global_load_dword v98, v87, s[48:49] sc0 sc1
	global_load_dword v228, v87, s[50:51] sc0 sc1
	s_cmp_lt_u32 s41, 2
	s_cselect_b32 s58, 0, 0x4000
	v_subrev_u32_e32 v87, s58, v82
	global_load_dword v99, v87, s[48:49] sc0 sc1
	global_load_dword v229, v87, s[50:51] sc0 sc1
	s_cmp_lt_u32 s41, 3
	s_cselect_b32 s58, 0, 0x6000
	v_subrev_u32_e32 v87, s58, v82
	global_load_dword v100, v87, s[48:49] sc0 sc1
	global_load_dword v230, v87, s[50:51] sc0 sc1
	s_cmp_lt_u32 s41, 4
	s_cselect_b32 s58, 0, 0x8000
	v_subrev_u32_e32 v87, s58, v82
	global_load_dword v101, v87, s[48:49] sc0 sc1
	global_load_dword v231, v87, s[50:51] sc0 sc1
	s_cmp_lt_u32 s41, 5
	s_cselect_b32 s58, 0, 0xa000
	v_subrev_u32_e32 v87, s58, v82
	global_load_dword v102, v87, s[48:49] sc0 sc1
	global_load_dword v232, v87, s[50:51] sc0 sc1
	s_cmp_lt_u32 s41, 6
	s_cselect_b32 s58, 0, 0xc000
	v_subrev_u32_e32 v87, s58, v82
	global_load_dword v103, v87, s[48:49] sc0 sc1
	global_load_dword v233, v87, s[50:51] sc0 sc1
	s_cmp_lt_u32 s41, 7
	s_cselect_b32 s58, 0, 0xe000
	v_subrev_u32_e32 v87, s58, v82
	global_load_dword v104, v87, s[48:49] sc0 sc1
	global_load_dword v234, v87, s[50:51] sc0 sc1
	s_cmp_lt_u32 s41, 8
	s_cselect_b32 s58, 0, 0x10000
	v_subrev_u32_e32 v87, s58, v82
	global_load_dword v105, v87, s[48:49] sc0 sc1
	global_load_dword v235, v87, s[50:51] sc0 sc1
	s_cmp_lt_u32 s41, 9
	s_cselect_b32 s58, 0, 0x12000
	v_subrev_u32_e32 v87, s58, v82
	global_load_dword v106, v87, s[48:49] sc0 sc1
	global_load_dword v236, v87, s[50:51] sc0 sc1
	s_cmp_lt_u32 s41, 10
	s_cselect_b32 s58, 0, 0x14000
	v_subrev_u32_e32 v87, s58, v82
	global_load_dword v107, v87, s[48:49] sc0 sc1
	global_load_dword v237, v87, s[50:51] sc0 sc1
	s_cmp_lt_u32 s41, 11
	s_cselect_b32 s58, 0, 0x16000
	v_subrev_u32_e32 v87, s58, v82
	global_load_dword v108, v87, s[48:49] sc0 sc1
	global_load_dword v238, v87, s[50:51] sc0 sc1
	s_cmp_lt_u32 s41, 12
	s_cselect_b32 s58, 0, 0x18000
	v_subrev_u32_e32 v87, s58, v82
	global_load_dword v109, v87, s[48:49] sc0 sc1
	global_load_dword v239, v87, s[50:51] sc0 sc1
	s_cmp_lt_u32 s41, 13
	s_cselect_b32 s58, 0, 0x1a000
	v_subrev_u32_e32 v87, s58, v82
	global_load_dword v110, v87, s[48:49] sc0 sc1
	global_load_dword v240, v87, s[50:51] sc0 sc1
	s_cmp_lt_u32 s41, 14
	s_cselect_b32 s58, 0, 0x1c000
	v_subrev_u32_e32 v87, s58, v82
	global_load_dword v111, v87, s[48:49] sc0 sc1
	global_load_dword v241, v87, s[50:51] sc0 sc1
	s_cmp_lt_u32 s41, 15
	s_cselect_b32 s58, 0, 0x1e000
	v_subrev_u32_e32 v87, s58, v82
	global_load_dword v112, v87, s[48:49] sc0 sc1
	global_load_dword v242, v87, s[50:51] sc0 sc1
	s_waitcnt vmcnt(0)
	v_mov_b32_e32 v70, v252
	s_cmp_lt_u32 s41, 15
	s_cbranch_scc1 LRUX_sk15
	v_fma_f32 v70, v112, v70, v242
LRUX_sk15:
	s_cmp_lt_u32 s41, 14
	s_cbranch_scc1 LRUX_sk14
	v_fma_f32 v70, v111, v70, v241
LRUX_sk14:
	s_cmp_lt_u32 s41, 13
	s_cbranch_scc1 LRUX_sk13
	v_fma_f32 v70, v110, v70, v240
LRUX_sk13:
	s_cmp_lt_u32 s41, 12
	s_cbranch_scc1 LRUX_sk12
	v_fma_f32 v70, v109, v70, v239
LRUX_sk12:
	s_cmp_lt_u32 s41, 11
	s_cbranch_scc1 LRUX_sk11
	v_fma_f32 v70, v108, v70, v238
LRUX_sk11:
	s_cmp_lt_u32 s41, 10
	s_cbranch_scc1 LRUX_sk10
	v_fma_f32 v70, v107, v70, v237
LRUX_sk10:
	s_cmp_lt_u32 s41, 9
	s_cbranch_scc1 LRUX_sk9
	v_fma_f32 v70, v106, v70, v236
LRUX_sk9:
	s_cmp_lt_u32 s41, 8
	s_cbranch_scc1 LRUX_sk8
	v_fma_f32 v70, v105, v70, v235
LRUX_sk8:
	s_cmp_lt_u32 s41, 7
	s_cbranch_scc1 LRUX_sk7
	v_fma_f32 v70, v104, v70, v234
LRUX_sk7:
	s_cmp_lt_u32 s41, 6
	s_cbranch_scc1 LRUX_sk6
	v_fma_f32 v70, v103, v70, v233
LRUX_sk6:
	s_cmp_lt_u32 s41, 5
	s_cbranch_scc1 LRUX_sk5
	v_fma_f32 v70, v102, v70, v232
LRUX_sk5:
	s_cmp_lt_u32 s41, 4
	s_cbranch_scc1 LRUX_sk4
	v_fma_f32 v70, v101, v70, v231
LRUX_sk4:
	s_cmp_lt_u32 s41, 3
	s_cbranch_scc1 LRUX_sk3
	v_fma_f32 v70, v100, v70, v230
LRUX_sk3:
	s_cmp_lt_u32 s41, 2
	s_cbranch_scc1 LRUX_sk2
	v_fma_f32 v70, v99, v70, v229
LRUX_sk2:
	s_cmp_lt_u32 s41, 1
	s_cbranch_scc1 LRUX_sk1
	v_fma_f32 v70, v98, v70, v228
LRUX_sk1:
	v_fma_f32 v252, v81, v70, v80
	s_and_saveexec_b64 s[4:5], s[2:3]
	s_cbranch_execz .LBB0_541
	s_mov_b64 s[24:25], 0
	v_mov_b32_e32 v68, v205
	v_mov_b32_e32 v69, v137
